# scan chunk loop edge: the prefetch gate falls through on the common path (no taken branch per chunk); rare no-load path moved out of line
# baseline (speedup 1.0000x reference)
; #define SC_GLOAD(ci_) { rg0 = SC_G1(ci_, 0); rg1 = SC_G1(ci_, 1); rg2 = SC_G1(ci_, 2); }
; __device__ __forceinline__ void rwkv_scan_unit(const Params& p, int unit, char* smem) {
;     ...
;         if (ci + 1 < NCH) { SC_GLOAD(ci + 1) }
.Lsc_p0:
	s_cmpk_ge_i32 s55, 0x10c0
	s_cbranch_scc1 .Lsc_p0_noload
	s_cmpk_ge_u32 s55, 0xc0
	s_movk_i32 s98, 0xff
	s_movk_i32 s99, 0x11ff
	s_cselect_b32 s98, s99, s98
	s_sub_u32 s98, s98, s55
	s_cmp_lg_u64 s[44:45], 0
	s_cselect_b32 s98, s55, s98
	s_lshl_b32 s98, s98, 9
	s_mov_b32 s99, 0
	v_lshl_add_u64 v[160:161], v[224:225], 0, s[98:99]
	global_load_dwordx4 v[160:163], v[160:161], off
	v_lshl_add_u64 v[164:165], v[226:227], 0, s[98:99]
	global_load_dwordx4 v[164:167], v[164:165], off
	v_lshl_add_u64 v[168:169], v[228:229], 0, s[98:99]
	global_load_dwordx4 v[168:171], v[168:169], off

; #define SC_GLOAD(ci_) { rg0 = SC_G1(ci_, 0); rg1 = SC_G1(ci_, 1); rg2 = SC_G1(ci_, 2); }
; __device__ __forceinline__ void rwkv_scan_unit(const Params& p, int unit, char* smem) {
;     ...
;         if (ci + 1 < NCH) { SC_GLOAD(ci + 1) }
.Lsc_p1:
	s_cmpk_ge_i32 s55, 0x10c0
	s_cbranch_scc1 .Lsc_p1_noload
	s_cmpk_ge_u32 s55, 0xc0
	s_movk_i32 s98, 0xff
	s_movk_i32 s99, 0x11ff
	s_cselect_b32 s98, s99, s98
	s_sub_u32 s98, s98, s55
	s_cmp_lg_u64 s[44:45], 0
	s_cselect_b32 s98, s55, s98
	s_lshl_b32 s98, s98, 9
	s_mov_b32 s99, 0
	v_lshl_add_u64 v[0:1], v[224:225], 0, s[98:99]
	global_load_dwordx4 v[0:3], v[0:1], off
	v_lshl_add_u64 v[4:5], v[226:227], 0, s[98:99]
	global_load_dwordx4 v[4:7], v[4:5], off
	v_lshl_add_u64 v[8:9], v[228:229], 0, s[98:99]
	global_load_dwordx4 v[8:11], v[8:9], off

; #define SC_GLOAD(ci_) { rg0 = SC_G1(ci_, 0); rg1 = SC_G1(ci_, 1); rg2 = SC_G1(ci_, 2); }
; __device__ __forceinline__ void rwkv_scan_unit(const Params& p, int unit, char* smem) {
;     ...
;         if (ci + 1 < NCH) { SC_GLOAD(ci + 1) }
.Lsc_p2:
	s_cmpk_ge_i32 s55, 0x10c0
	s_cbranch_scc1 .Lsc_p2_noload
	s_cmpk_ge_u32 s55, 0xc0
	s_movk_i32 s98, 0xff
	s_movk_i32 s99, 0x11ff
	s_cselect_b32 s98, s99, s98
	s_sub_u32 s98, s98, s55
	s_cmp_lg_u64 s[44:45], 0
	s_cselect_b32 s98, s55, s98
	s_lshl_b32 s98, s98, 9
	s_mov_b32 s99, 0
	v_lshl_add_u64 v[140:141], v[224:225], 0, s[98:99]
	global_load_dwordx4 v[140:143], v[140:141], off
	v_lshl_add_u64 v[144:145], v[226:227], 0, s[98:99]
	global_load_dwordx4 v[144:147], v[144:145], off
	v_lshl_add_u64 v[148:149], v[228:229], 0, s[98:99]
	global_load_dwordx4 v[148:151], v[148:149], off

; #define SC_GLOAD(ci_) { rg0 = SC_G1(ci_, 0); rg1 = SC_G1(ci_, 1); rg2 = SC_G1(ci_, 2); }
; __device__ __forceinline__ void rwkv_scan_unit(const Params& p, int unit, char* smem) {
;     ...
;         if (ci + 1 < NCH) { SC_GLOAD(ci + 1) }
.Lsc_p3:
	s_cmpk_ge_i32 s55, 0x10c0
	s_cbranch_scc1 .Lsc_p3_noload
	s_cmpk_ge_u32 s55, 0xc0
	s_movk_i32 s98, 0xff
	s_movk_i32 s99, 0x11ff
	s_cselect_b32 s98, s99, s98
	s_sub_u32 s98, s98, s55
	s_cmp_lg_u64 s[44:45], 0
	s_cselect_b32 s98, s55, s98
	s_lshl_b32 s98, s98, 9
	s_mov_b32 s99, 0
	v_lshl_add_u64 v[124:125], v[224:225], 0, s[98:99]
	global_load_dwordx4 v[124:127], v[124:125], off
	v_lshl_add_u64 v[128:129], v[226:227], 0, s[98:99]
	global_load_dwordx4 v[128:131], v[128:129], off
	v_lshl_add_u64 v[132:133], v[228:229], 0, s[98:99]
	global_load_dwordx4 v[132:135], v[132:133], off

; #define SC_GLOAD(ci_) { rg0 = SC_G1(ci_, 0); rg1 = SC_G1(ci_, 1); rg2 = SC_G1(ci_, 2); }
; __device__ __forceinline__ void rwkv_scan_unit(const Params& p, int unit, char* smem) {
;     ...
;         if (ci + 1 < NCH) { SC_GLOAD(ci + 1) }
.Lsc_p0_noload:
	s_waitcnt vmcnt(0)
	s_branch .Lsc_p0_body
